# v1 + hg2/rt2 norm-gain loads issued together (were 4 serial round trips), hg2 dir-1 state tile requested at item start
# speedup vs baseline: 1.0100x; 1.0100x over previous
; #define LAS __attribute__((address_space(3)))
; #define BAR_LDS() do { asm volatile("s_waitcnt lgkmcnt(0)" ::: "memory"); __builtin_amdgcn_s_barrier(); asm volatile("" ::: "memory"); } while (0)
; __device__ __forceinline__ float bf2f(unsigned h) { return __uint_as_float(h << 16); }
; __device__ __forceinline__ unsigned pk2(float lo, float hi) { return pg8::cvt_pk_bf16(lo, hi); }
; template <int DK, bool RET>
; __device__ __forceinline__ void gla_out_item(const Ctx& X, const bf16* H, bf16* Y, int l, int r, OutRegs<RET>& R, bool has_next) {
;     ...
;     const float rstd = __builtin_amdgcn_rsqf((red[X.wave * 16 + fr] + red[(X.wave ^ 4) * 16 + fr]) * (1.0f / 128.0f) + EPS);
;     const float* gn = X.in(RET ? 10 : 9) + l * 768 + head * 128;
; #pragma unroll
;     for (int t = 0; t < 4; ++t) { const int v = 64 * vh + 16 * t + 4 * fq; const f32x4 g4 = *(const f32x4*)(gn + v);
;         const float g0 = bf2f(gw[t].x & 0xffffu), g1 = bf2f(gw[t].x >> 16), g2 = bf2f(gw[t].y & 0xffffu), g3 = bf2f(gw[t].y >> 16);
;         const float y0 = (o[t][0] - mu) * rstd * g4.x * (g0 * __builtin_amdgcn_rcpf(1.0f + __expf(-g0))), y1 = (o[t][1] - mu) * rstd * g4.y * (g1 * __builtin_amdgcn_rcpf(1.0f + __expf(-g1)));
;         const float y2 = (o[t][2] - mu) * rstd * g4.z * (g2 * __builtin_amdgcn_rcpf(1.0f + __expf(-g2))), y3 = (o[t][3] - mu) * rstd * g4.w * (g3 * __builtin_amdgcn_rcpf(1.0f + __expf(-g3)));
;         v2u w; w.x = pk2(y0, y1); w.y = pk2(y2, y3); *(LAS v2u*)(X.lds + L::Q0 + (16 * tb + fr) * 272 + v * 2) = w; }
;     BAR_LDS();
;     { const size_t mrow = (size_t)(b * SEQ + n * CH); int t_ = X.tid; asm volatile("" : "+v"(t_));
; #pragma unroll
;         for (int p = 0; p < 2; ++p) { const int idx = t_ + NTHR * p, row = idx >> 4, c8 = idx & 15; *(v4u*)(Y + (mrow + row) * D + ycol + 8 * c8) = *(const LAS v4u*)(X.lds + L::Q0 + row * 272 + c8 * 16); } }
;     BAR_LDS();
.LBB0_477:
	s_or_b64 exec, exec, s[0:1]
	s_waitcnt lgkmcnt(0)
	s_barrier
	s_waitcnt vmcnt(0)
	ds_read_b32 v61, v120
	s_waitcnt lgkmcnt(1)
	ds_read_b32 v63, v121
	s_load_dwordx2 s[0:1], s[18:19], 0x48
	v_lshlrev_b32_e32 v80, 16, v72
	v_and_b32_e32 v81, 0xffff0000, v72
	v_lshlrev_b32_e32 v72, 16, v73
	s_waitcnt lgkmcnt(0)
	v_add_f32_e32 v61, v61, v63
	s_add_u32 s0, s0, s28
	s_addc_u32 s1, s1, s29
	s_add_u32 s0, s0, s12
	s_addc_u32 s1, s1, s13
	v_lshl_add_u64 v[74:75], v[58:59], 2, s[0:1]
	global_load_dwordx4 v[76:79], v[74:75], off
	global_load_dwordx4 v[200:203], v[74:75], off offset:64
	global_load_dwordx4 v[204:207], v[74:75], off offset:128
	global_load_dwordx4 v[208:211], v[74:75], off offset:192
	v_fmamk_f32 v61, v61, 0x3c000000, v1
	v_rsq_f32_e32 v66, v61
	v_mul_f32_e32 v61, 0xbfb8aa3b, v80
	v_exp_f32_e32 v61, v61
	v_and_b32_e32 v73, 0xffff0000, v73
	v_pk_mul_f32 v[38:39], v[38:39], v[66:67] op_sel_hi:[1,0]
	v_pk_mul_f32 v[40:41], v[40:41], v[66:67] op_sel_hi:[1,0]
	v_add_f32_e32 v61, 1.0, v61
	v_rcp_f32_e32 v82, v61
	v_mul_f32_e32 v61, 0xbfb8aa3b, v81
	v_exp_f32_e32 v61, v61
	v_pk_mul_f32 v[34:35], v[34:35], v[66:67] op_sel_hi:[1,0]
	v_pk_mul_f32 v[36:37], v[36:37], v[66:67] op_sel_hi:[1,0]
	v_pk_mul_f32 v[30:31], v[30:31], v[66:67] op_sel_hi:[1,0]
	v_add_f32_e32 v61, 1.0, v61
	v_rcp_f32_e32 v83, v61
	v_mul_f32_e32 v61, 0xbfb8aa3b, v72
	v_exp_f32_e32 v61, v61
	v_pk_mul_f32 v[32:33], v[32:33], v[66:67] op_sel_hi:[1,0]
	v_pk_mul_f32 v[26:27], v[26:27], v[66:67] op_sel_hi:[1,0]
	v_pk_mul_f32 v[28:29], v[28:29], v[66:67] op_sel_hi:[1,0]
	v_add_f32_e32 v61, 1.0, v61
	s_lshl_b64 s[0:1], s[14:15], 1
	s_add_u32 s0, s75, s0
	s_addc_u32 s1, s76, s1
	s_add_i32 s80, s80, s79
	s_and_b64 vcc, exec, s[4:5]
	s_waitcnt vmcnt(3)
	v_pk_mul_f32 v[38:39], v[76:77], v[38:39]
	v_pk_mul_f32 v[76:77], v[82:83], v[80:81]
	v_pk_mul_f32 v[40:41], v[78:79], v[40:41]
	v_pk_mul_f32 v[38:39], v[76:77], v[38:39]
	v_rcp_f32_e32 v76, v61
	v_mul_f32_e32 v61, 0xbfb8aa3b, v73
	v_exp_f32_e32 v61, v61
	v_cvt_pk_bf16_f32 v38, v38, v39
	v_add_f32_e32 v61, 1.0, v61
	v_rcp_f32_e32 v77, v61
	s_nop 0
	v_pk_mul_f32 v[72:73], v[76:77], v[72:73]
	s_nop 0
	v_pk_mul_f32 v[40:41], v[72:73], v[40:41]
	v_lshlrev_b32_e32 v72, 16, v70
	v_cvt_pk_bf16_f32 v39, v40, v41
	v_add_u32_e32 v40, v122, v123
	ds_write_b64 v40, v[38:39]
	v_and_b32_e32 v73, 0xffff0000, v70
	v_mul_f32_e32 v61, 0xbfb8aa3b, v72
	v_exp_f32_e32 v61, v61
	s_waitcnt vmcnt(2)
	v_pk_mul_f32 v[34:35], v[34:35], v[200:201]
	v_mul_f32_e32 v38, 0xbfb8aa3b, v73
	v_exp_f32_e32 v38, v38
	v_add_f32_e32 v61, 1.0, v61
	v_rcp_f32_e32 v76, v61
	v_pk_mul_f32 v[36:37], v[36:37], v[202:203]
	v_add_f32_e32 v38, 1.0, v38
	v_rcp_f32_e32 v77, v38
	s_nop 0
	v_pk_mul_f32 v[38:39], v[76:77], v[72:73]
	s_nop 0
	v_pk_mul_f32 v[34:35], v[38:39], v[34:35]
	v_lshlrev_b32_e32 v38, 16, v71
	v_and_b32_e32 v39, 0xffff0000, v71
	v_mul_f32_e32 v61, 0xbfb8aa3b, v38
	v_mul_f32_e32 v40, 0xbfb8aa3b, v39
	v_exp_f32_e32 v61, v61
	v_exp_f32_e32 v40, v40
	v_cvt_pk_bf16_f32 v34, v34, v35
	v_add_f32_e32 v61, 1.0, v61
	v_add_f32_e32 v40, 1.0, v40
	v_rcp_f32_e32 v70, v61
	v_rcp_f32_e32 v71, v40
	s_nop 0
	v_pk_mul_f32 v[38:39], v[70:71], v[38:39]
	s_nop 0
	v_pk_mul_f32 v[36:37], v[38:39], v[36:37]
	v_lshlrev_b32_e32 v38, 16, v68
	v_cvt_pk_bf16_f32 v35, v36, v37
	ds_write_b64 v137, v[34:35]
	v_and_b32_e32 v39, 0xffff0000, v68
	v_mul_f32_e32 v40, 0xbfb8aa3b, v38
	v_exp_f32_e32 v40, v40
	s_waitcnt vmcnt(1)
	v_pk_mul_f32 v[30:31], v[30:31], v[204:205]
	v_mul_f32_e32 v34, 0xbfb8aa3b, v39
	v_exp_f32_e32 v34, v34
	v_add_f32_e32 v40, 1.0, v40
	v_rcp_f32_e32 v40, v40
	v_pk_mul_f32 v[32:33], v[32:33], v[206:207]
	v_add_f32_e32 v34, 1.0, v34
	v_rcp_f32_e32 v41, v34
	s_nop 0
	v_pk_mul_f32 v[34:35], v[40:41], v[38:39]
	s_nop 0
	v_pk_mul_f32 v[30:31], v[34:35], v[30:31]
	v_lshlrev_b32_e32 v34, 16, v69
	v_and_b32_e32 v35, 0xffff0000, v69
	v_mul_f32_e32 v38, 0xbfb8aa3b, v34
	v_mul_f32_e32 v36, 0xbfb8aa3b, v35
	v_exp_f32_e32 v38, v38
	v_exp_f32_e32 v36, v36
	v_cvt_pk_bf16_f32 v30, v30, v31
	v_add_f32_e32 v38, 1.0, v38
	v_add_f32_e32 v36, 1.0, v36
	v_rcp_f32_e32 v38, v38
	v_rcp_f32_e32 v39, v36
	s_nop 0
	v_pk_mul_f32 v[34:35], v[38:39], v[34:35]
	s_nop 0
	v_pk_mul_f32 v[32:33], v[34:35], v[32:33]
	v_lshlrev_b32_e32 v34, 16, v64
	v_cvt_pk_bf16_f32 v31, v32, v33
	ds_write_b64 v138, v[30:31]
	v_and_b32_e32 v35, 0xffff0000, v64
	v_mul_f32_e32 v36, 0xbfb8aa3b, v34
	v_exp_f32_e32 v36, v36
	s_waitcnt vmcnt(0)
	v_pk_mul_f32 v[26:27], v[26:27], v[208:209]
	v_mul_f32_e32 v30, 0xbfb8aa3b, v35
	v_exp_f32_e32 v30, v30
	v_add_f32_e32 v36, 1.0, v36
	v_rcp_f32_e32 v36, v36
	v_pk_mul_f32 v[28:29], v[28:29], v[210:211]
	v_add_f32_e32 v30, 1.0, v30
	v_rcp_f32_e32 v37, v30
	s_nop 0
	v_pk_mul_f32 v[30:31], v[36:37], v[34:35]
	s_nop 0
	v_pk_mul_f32 v[26:27], v[30:31], v[26:27]
	v_lshlrev_b32_e32 v30, 16, v65
	v_and_b32_e32 v31, 0xffff0000, v65
	v_mul_f32_e32 v34, 0xbfb8aa3b, v30
	v_mul_f32_e32 v32, 0xbfb8aa3b, v31
	v_exp_f32_e32 v34, v34
	v_exp_f32_e32 v32, v32
	v_cvt_pk_bf16_f32 v26, v26, v27
	v_add_f32_e32 v34, 1.0, v34
	v_add_f32_e32 v32, 1.0, v32
	v_rcp_f32_e32 v34, v34
	v_rcp_f32_e32 v35, v32
	s_nop 0
	v_pk_mul_f32 v[30:31], v[34:35], v[30:31]
	s_nop 0
	v_pk_mul_f32 v[28:29], v[30:31], v[28:29]
	v_mov_b32_e32 v34, v42
	v_cvt_pk_bf16_f32 v27, v28, v29
	ds_write_b64 v139, v[26:27]
	s_waitcnt lgkmcnt(0)
	s_barrier
	s_nop 0
	v_lshlrev_b32_e32 v26, 4, v34
	v_ashrrev_i32_e32 v32, 4, v34
	v_and_b32_e32 v158, 0xf0, v26
	v_mul_lo_u32 v26, v32, s27
	v_add3_u32 v26, 0, v26, v158
	ds_read_b128 v[26:29], v26
	v_ashrrev_i32_e32 v33, 31, v32
	v_lshl_add_u64 v[32:33], v[32:33], 0, s[68:69]
	v_lshl_add_u64 v[30:31], s[0:1], 0, v[158:159]
	v_lshlrev_b64 v[32:33], 12, v[32:33]
	v_lshl_add_u64 v[32:33], v[30:31], 0, v[32:33]
	s_waitcnt lgkmcnt(0)
	global_store_dwordx4 v[32:33], v[26:29], off
	s_mov_b32 s0, s81
	s_nop 0
	v_add_u32_e32 v26, 0x200, v34
	v_ashrrev_i32_e32 v32, 4, v26
	v_mul_lo_u32 v26, v32, s27
	v_add3_u32 v26, 0, v26, v158
	ds_read_b128 v[26:29], v26
	v_ashrrev_i32_e32 v33, 31, v32
	v_lshl_add_u64 v[32:33], v[32:33], 0, s[68:69]
	v_lshlrev_b64 v[32:33], 12, v[32:33]
	v_lshl_add_u64 v[30:31], v[30:31], 0, v[32:33]
	s_waitcnt lgkmcnt(0)
	global_store_dwordx4 v[30:31], v[26:29], off
	s_waitcnt lgkmcnt(0)
	s_barrier
	s_cbranch_vccnz .LBB0_566

; #define LAS __attribute__((address_space(3)))
; #define SP_BEGIN() unsigned long long sp0_ = 0; if (PROBE_MASK >> 16) sp0_ = __builtin_amdgcn_s_memrealtime();
; __device__ __forceinline__ f32x2v bfpair(unsigned w) { f32x2v r; r.x = __uint_as_float(w << 16); r.y = __uint_as_float(w & 0xffff0000u); return r; }
; __device__ __forceinline__ f32x2v rcp2(f32x2v v) { f32x2v r; r.x = __builtin_amdgcn_rcpf(v.x); r.y = __builtin_amdgcn_rcpf(v.y); return r; }
; template <int DIR, bool NEEDQ>
; __device__ __forceinline__ void gla_prep(lptr rawz, lptr rawq, f32x2v lb, LAS float* seg, int kp, int rg, f32x2v (&c)[8], f32x2v (&qv)[8], f32x2v (&kv)[8]) {
;     f32x2v run = (f32x2v){1.f, 1.f}; const f32x2v oml = 1.0f - lb;
; #pragma unroll
;     for (int i = 0; i < 8; ++i) { const int ii = DIR ? 7 - i : i; const int r = 8 * rg + ii;
;         const f32x2v z = bfpair(*(const LAS unsigned*)(rawz + (r * 128 + 2 * kp) * 2)); f32x2v e; e.x = __expf(-z.x); e.y = __expf(-z.y);
;         const f32x2v f = lb + oml * rcp2(e + 1.0f); run = run * f; kv[ii] = 1.0f - f; c[ii] = run;
;         if (NEEDQ) qv[ii] = bfpair(*(const LAS unsigned*)(rawq + (r * 128 + 2 * kp) * 2)); }
;     *(LAS f32x2v*)(seg + rg * 128 + 2 * kp) = run;
; }
; template <int DK, bool RET, int DIR>
; __device__ __forceinline__ void gla_out_dir(const Ctx& X, int chain, int n, f32x2v lb, const unsigned char* St, f32x4 (&o)[4], const bf16* H, size_t m0, int zbcol) {
;     ...
;     SP_BEGIN()
;     const unsigned char* Sp = St + ((size_t)chain * NCH + n) * 128 * DK;
;     v4u sr[2];
; #pragma unroll
;     for (int p = 0; p < 2; ++p) { const int idx = X.tid + NTHR * p; sr[p] = *(const v4u*)(Sp + (size_t)idx * 16); }
;     {
;         f32x2v c[8], qv[8], kv[8];
;         gla_prep<DIR, true>(rawz, rawq, lb, seg, kp, rg, c, qv, kv);
.LBB0_480:
	s_mul_hi_i32 s60, s0, 0x2aaaaaab
	s_lshr_b32 s61, s60, 31
	s_ashr_i32 s84, s60, 7
	s_lshl_b32 s60, s83, 7
	s_add_i32 s84, s84, s61
	s_sub_i32 s0, s0, s60
	s_mul_i32 s60, s84, 6
	s_add_i32 s60, s60, s1
	s_lshl_b32 s62, s60, 1
	s_ashr_i32 s63, s62, 31
	s_ashr_i32 s1, s0, 31
	s_lshl_b64 s[0:1], s[0:1], 14
	s_lshl_b64 s[68:69], s[62:63], 21
	s_add_u32 s61, s77, s68
	s_addc_u32 s63, s78, s69
	s_add_u32 s68, s61, s0
	s_addc_u32 s69, s63, s1
	v_mov_b32_e32 v35, v42
	v_lshl_add_u64 v[26:27], s[68:69], 0, v[54:55]
	s_waitcnt lgkmcnt(0)
	s_barrier
	global_load_dwordx4 v[30:33], v[26:27], off
	v_lshl_add_u64 v[26:27], s[68:69], 0, v[56:57]
	global_load_dwordx4 v[26:29], v[26:27], off
	s_add_u32 s98, s68, 0x200000
	s_addc_u32 s99, s69, 0
	v_lshl_add_u64 v[220:221], s[98:99], 0, v[54:55]
	global_load_dwordx4 v[212:215], v[220:221], off
	v_lshl_add_u64 v[220:221], s[98:99], 0, v[56:57]
	global_load_dwordx4 v[216:219], v[220:221], off
	v_readfirstlane_b32 s60, v35
	v_and_b32_e32 v90, 63, v35
	s_ashr_i32 s61, s60, 6
	v_lshlrev_b32_e32 v35, 2, v90
	v_lshl_or_b32 v91, s61, 11, v35
	s_add_i32 s63, 0, 0x14c00
	v_add_u32_e32 v36, s63, v91
	ds_read_b32 v36, v36
	s_add_i32 s82, 0, 0x18c00
	v_or_b32_e32 v40, 0x100, v91
	v_or_b32_e32 v68, 0x200, v91
	v_or_b32_e32 v74, 0x300, v91
	s_waitcnt lgkmcnt(0)
	v_lshlrev_b32_e32 v37, 16, v36
	v_and_b32_e32 v38, 0xffff0000, v36
	v_mul_f32_e32 v36, 0xbfb8aa3b, v37
	v_mul_f32_e32 v37, 0xbfb8aa3b, v38
	v_add_u32_e32 v38, s82, v91
	v_or_b32_e32 v78, 0x400, v91
	v_or_b32_e32 v80, 0x500, v91
	v_or_b32_e32 v96, 0x600, v91
	v_or_b32_e32 v91, 0x700, v91
	v_add_u32_e32 v98, s63, v91
	ds_read_b32 v61, v38
	ds_read_b32 v98, v98
	v_add_u32_e32 v38, s63, v40
	v_add_u32_e32 v40, s82, v40
	ds_read_b32 v38, v38
	ds_read_b32 v93, v40
	v_add_u32_e32 v40, s63, v68
	v_add_u32_e32 v68, s82, v68
	ds_read_b32 v40, v40
	ds_read_b32 v92, v68
	v_add_u32_e32 v68, s63, v74
	v_add_u32_e32 v74, s82, v74
	ds_read_b32 v68, v68
	ds_read_b32 v94, v74
	v_add_u32_e32 v74, s63, v78
	v_add_u32_e32 v78, s82, v78
	ds_read_b32 v74, v74
	ds_read_b32 v95, v78
	v_add_u32_e32 v78, s63, v80
	v_add_u32_e32 v80, s82, v80
	ds_read_b32 v78, v78
	ds_read_b32 v97, v80
	v_add_u32_e32 v80, s63, v96
	s_waitcnt lgkmcnt(9)
	v_lshlrev_b32_e32 v39, 16, v38
	v_and_b32_e32 v41, 0xffff0000, v38
	ds_read_b32 v80, v80
	v_mul_f32_e32 v38, 0xbfb8aa3b, v39
	v_mul_f32_e32 v39, 0xbfb8aa3b, v41
	s_waitcnt lgkmcnt(8)
	v_lshlrev_b32_e32 v41, 16, v40
	v_and_b32_e32 v64, 0xffff0000, v40
	v_exp_f32_e32 v36, v36
	v_exp_f32_e32 v37, v37
	v_exp_f32_e32 v38, v38
	v_exp_f32_e32 v39, v39
	v_mul_f32_e32 v40, 0xbfb8aa3b, v41
	v_mul_f32_e32 v41, 0xbfb8aa3b, v64
	s_waitcnt lgkmcnt(6)
	v_lshlrev_b32_e32 v69, 16, v68
	v_and_b32_e32 v72, 0xffff0000, v68
	v_exp_f32_e32 v40, v40
	v_exp_f32_e32 v41, v41
	v_mul_f32_e32 v68, 0xbfb8aa3b, v69
	v_mul_f32_e32 v69, 0xbfb8aa3b, v72
	s_waitcnt lgkmcnt(4)
	v_lshlrev_b32_e32 v75, 16, v74
	v_and_b32_e32 v76, 0xffff0000, v74
	v_exp_f32_e32 v68, v68
	v_exp_f32_e32 v69, v69
	v_mul_f32_e32 v74, 0xbfb8aa3b, v75
	v_mul_f32_e32 v75, 0xbfb8aa3b, v76
	s_waitcnt lgkmcnt(2)
	v_lshlrev_b32_e32 v79, 16, v78
	v_and_b32_e32 v81, 0xffff0000, v78
	v_add_u32_e32 v96, s82, v96
	v_exp_f32_e32 v74, v74
	v_exp_f32_e32 v75, v75
	v_mul_f32_e32 v78, 0xbfb8aa3b, v79
	v_mul_f32_e32 v79, 0xbfb8aa3b, v81
	ds_read_b32 v96, v96
	s_waitcnt lgkmcnt(1)
	v_lshlrev_b32_e32 v81, 16, v80
	v_and_b32_e32 v82, 0xffff0000, v80
	v_pk_add_f32 v[36:37], v[36:37], 1.0 op_sel_hi:[1,0]
	v_pk_add_f32 v[38:39], v[38:39], 1.0 op_sel_hi:[1,0]
	v_exp_f32_e32 v78, v78
	v_exp_f32_e32 v79, v79
	v_mul_f32_e32 v80, 0xbfb8aa3b, v81
	v_mul_f32_e32 v81, 0xbfb8aa3b, v82
	v_lshlrev_b32_e32 v99, 16, v98
	v_and_b32_e32 v100, 0xffff0000, v98
	v_rcp_f32_e32 v36, v36
	v_rcp_f32_e32 v37, v37
	v_rcp_f32_e32 v38, v38
	v_rcp_f32_e32 v39, v39
	v_pk_add_f32 v[40:41], v[40:41], 1.0 op_sel_hi:[1,0]
	v_exp_f32_e32 v80, v80
	v_exp_f32_e32 v81, v81
	v_mul_f32_e32 v98, 0xbfb8aa3b, v99
	v_mul_f32_e32 v99, 0xbfb8aa3b, v100
	v_rcp_f32_e32 v40, v40
	v_rcp_f32_e32 v41, v41
	v_pk_add_f32 v[68:69], v[68:69], 1.0 op_sel_hi:[1,0]
	v_exp_f32_e32 v98, v98
	v_exp_f32_e32 v99, v99
	v_rcp_f32_e32 v68, v68
	v_rcp_f32_e32 v69, v69
	v_pk_add_f32 v[74:75], v[74:75], 1.0 op_sel_hi:[1,0]
	v_pk_add_f32 v[88:89], v[86:87], 1.0 op_sel_hi:[1,0] neg_lo:[1,0] neg_hi:[1,0]
	v_rcp_f32_e32 v74, v74
	v_rcp_f32_e32 v75, v75
	v_pk_add_f32 v[78:79], v[78:79], 1.0 op_sel_hi:[1,0]
	v_pk_fma_f32 v[36:37], v[88:89], v[36:37], v[86:87]
	v_pk_fma_f32 v[70:71], v[88:89], v[38:39], v[86:87]
	v_rcp_f32_e32 v78, v78
	v_rcp_f32_e32 v79, v79
	v_pk_add_f32 v[80:81], v[80:81], 1.0 op_sel_hi:[1,0]
	v_pk_mul_f32 v[38:39], v[36:37], v[70:71]
	v_pk_fma_f32 v[64:65], v[88:89], v[40:41], v[86:87]
	v_rcp_f32_e32 v80, v80
	v_rcp_f32_e32 v81, v81
	v_pk_add_f32 v[98:99], v[98:99], 1.0 op_sel_hi:[1,0]
	v_pk_mul_f32 v[40:41], v[38:39], v[64:65]
	v_pk_fma_f32 v[72:73], v[88:89], v[68:69], v[86:87]
	v_rcp_f32_e32 v98, v98
	v_rcp_f32_e32 v99, v99
	v_pk_mul_f32 v[68:69], v[40:41], v[72:73]
	v_pk_fma_f32 v[76:77], v[88:89], v[74:75], v[86:87]
	v_pk_fma_f32 v[84:85], v[88:89], v[78:79], v[86:87]
	v_pk_mul_f32 v[74:75], v[68:69], v[76:77]
	v_pk_fma_f32 v[82:83], v[88:89], v[80:81], v[86:87]
	v_pk_mul_f32 v[78:79], v[74:75], v[84:85]
	s_lshl_b32 s68, s61, 9
	v_pk_mul_f32 v[80:81], v[78:79], v[82:83]
	v_pk_fma_f32 v[88:89], v[88:89], v[98:99], v[86:87]
	s_add_i32 s68, s74, s68
	v_lshlrev_b32_e32 v99, 3, v90
	v_pk_mul_f32 v[86:87], v[80:81], v[88:89]
	v_add_u32_e32 v91, s82, v91
	v_add_u32_e32 v90, s68, v99
	ds_read_b32 v98, v91
	ds_write_b64 v90, v[86:87]
	s_waitcnt vmcnt(3)
	v_cvt_pk_f32_fp8_e32 v[90:91], v30
	s_waitcnt lgkmcnt(0)
	s_barrier
; #define LAS __attribute__((address_space(3)))
; __device__ __forceinline__ unsigned pk2(float lo, float hi) { return pg8::cvt_pk_bf16(lo, hi); }
; __device__ __forceinline__ f32x2v f8lo(unsigned w) { return __builtin_amdgcn_cvt_pk_f32_fp8((int)w, false); }
; __device__ __forceinline__ f32x2v f8hi(unsigned w) { return __builtin_amdgcn_cvt_pk_f32_fp8((int)w, true); }
; template <int DK, bool RET, int DIR>
; __device__ __forceinline__ void gla_out_dir(const Ctx& X, int chain, int n, f32x2v lb, const unsigned char* St, f32x4 (&o)[4], const bf16* H, size_t m0, int zbcol) {
;     ...
;         for (int p = 0; p < 2; ++p) { const int idx = X.tid + NTHR * p; const lptr d = ST + (idx >> 3) * 272 + (idx & 7) * 32;
;             v4u a, b; f32x2v f;
;             f = f8lo(sr[p].x); a.x = pk2(f.x, f.y); f = f8hi(sr[p].x); a.y = pk2(f.x, f.y); f = f8lo(sr[p].y); a.z = pk2(f.x, f.y); f = f8hi(sr[p].y); a.w = pk2(f.x, f.y);
;             f = f8lo(sr[p].z); b.x = pk2(f.x, f.y); f = f8hi(sr[p].z); b.y = pk2(f.x, f.y); f = f8lo(sr[p].w); b.z = pk2(f.x, f.y); f = f8hi(sr[p].w); b.w = pk2(f.x, f.y);
;             *(LAS v4u*)d = a; *(LAS v4u*)(d + 16) = b; }
;         {
;             const int sg = DIR ? 7 - rg : rg, ss = sg >> 2, hq = sg & 3;
;             const f32x2v T0 = SEGT(0), T1 = SEGT(1), T2 = SEGT(2), T3 = SEGT(3), sub0 = (T0 * T1) * (T2 * T3);
;             f32x2v pq = (f32x2v){1.f, 1.f};
; #pragma unroll
;             for (int j = 0; j < 3; ++j) if (j < hq) pq = pq * SEGT(4 * ss + j);
	v_cvt_pk_bf16_f32 v100, v90, v91
	v_cvt_pk_f32_fp8_sdwa v[90:91], v30 src0_sel:WORD_1
	s_and_b32 s68, s61, 3
	s_and_b32 s69, s61, -4
	s_cmp_eq_u32 s68, 0
	v_cvt_pk_bf16_f32 v101, v90, v91
	v_cvt_pk_f32_fp8_e32 v[90:91], v31
	v_cvt_pk_f32_fp8_sdwa v[30:31], v31 src0_sel:WORD_1
	v_cvt_pk_bf16_f32 v102, v90, v91
	v_cvt_pk_bf16_f32 v103, v30, v31
	v_cvt_pk_f32_fp8_e32 v[30:31], v32
	v_cvt_pk_f32_fp8_sdwa v[90:91], v32 src0_sel:WORD_1
	v_cvt_pk_bf16_f32 v30, v30, v31
	v_cvt_pk_bf16_f32 v31, v90, v91
	v_cvt_pk_f32_fp8_e32 v[90:91], v33
	v_cvt_pk_bf16_f32 v32, v90, v91
	v_cvt_pk_f32_fp8_sdwa v[90:91], v33 src0_sel:WORD_1
	v_cvt_pk_bf16_f32 v33, v90, v91
	ds_write_b128 v140, v[100:103]
	ds_write_b128 v140, v[30:33] offset:16
	s_waitcnt vmcnt(2)
	v_cvt_pk_f32_fp8_e32 v[30:31], v26
	v_cvt_pk_f32_fp8_sdwa v[32:33], v26 src0_sel:WORD_1
	v_cvt_pk_f32_fp8_sdwa v[90:91], v28 src0_sel:WORD_1
	v_cvt_pk_bf16_f32 v30, v30, v31
	v_cvt_pk_bf16_f32 v31, v32, v33
	v_cvt_pk_f32_fp8_e32 v[32:33], v27
	v_cvt_pk_f32_fp8_sdwa v[26:27], v27 src0_sel:WORD_1
	v_cvt_pk_bf16_f32 v32, v32, v33
	v_cvt_pk_bf16_f32 v33, v26, v27
	v_cvt_pk_f32_fp8_e32 v[26:27], v28
	v_cvt_pk_bf16_f32 v26, v26, v27
	v_cvt_pk_bf16_f32 v27, v90, v91
	v_cvt_pk_f32_fp8_e32 v[90:91], v29
	v_cvt_pk_bf16_f32 v28, v90, v91
	v_cvt_pk_f32_fp8_sdwa v[90:91], v29 src0_sel:WORD_1
	v_cvt_pk_bf16_f32 v29, v90, v91
	ds_write_b128 v141, v[30:33]
	ds_write_b128 v141, v[26:29] offset:16
	v_add_u32_e32 v29, 0, v99
	v_add_u32_e32 v28, s74, v99
	v_add_u32_e32 v30, 0x13a00, v29
	v_add_u32_e32 v32, 0x13c00, v29
	v_add_u32_e32 v29, 0x13e00, v29
	ds_read_b64 v[26:27], v28
	ds_read_b64 v[30:31], v30
	ds_read_b64 v[32:33], v32
	ds_read_b64 v[90:91], v29
	v_lshl_add_u32 v99, s69, 9, v28
	s_cbranch_scc1 .LBB0_564
	ds_read_b64 v[28:29], v99
	s_cmp_lt_u32 s68, 2
	s_cbranch_scc1 .LBB0_483

; #define SP_BEGIN() unsigned long long sp0_ = 0; if (PROBE_MASK >> 16) sp0_ = __builtin_amdgcn_s_memrealtime();
; #define MFMA16(a, b, c) __builtin_amdgcn_mfma_f32_16x16x32_bf16((a), (b), (c), 0, 0, 0)
; template <int DK, bool RET, int DIR>
; __device__ __forceinline__ void gla_out_dir(const Ctx& X, int chain, int n, f32x2v lb, const unsigned char* St, f32x4 (&o)[4], const bf16* H, size_t m0, int zbcol) {
;     ...
;     SP_BEGIN()
;     const unsigned char* Sp = St + ((size_t)chain * NCH + n) * 128 * DK;
;     v4u sr[2];
; #pragma unroll
;     for (int p = 0; p < 2; ++p) { const int idx = X.tid + NTHR * p; sr[p] = *(const v4u*)(Sp + (size_t)idx * 16); }
;     {
;         f32x2v c[8], qv[8], kv[8];
;         gla_prep<DIR, true>(rawz, rawq, lb, seg, kp, rg, c, qv, kv);
;     ...
;         const int stb = DIR ? 3 - tb : tb; const int r = 16 * tb + fr;
; #pragma unroll
;         for (int ks = 0; ks < 2; ++ks) { const bf16x8 bb = ldsfrag(AM, r, 144, 32 * ks + 8 * fq);
; #pragma unroll
;             for (int vt = 0; vt < 4; ++vt) { const bf16x8 a = vtfrag(VT, 64 * vh + 16 * vt + fr, 144, 32 * ks + 8 * fq); o[vt] = MFMA16(a, bb, o[vt]); } }
;         const lptr QI = (stb >> 1) ? Q1 : Q0; const int qrow = (stb >> 1) ? (DIR ? r : r - 32) : r;
; #pragma unroll
;         for (int ks = 0; ks < DK / 32; ++ks) { const bf16x8 bb = ldsfrag(QI, qrow, SQ, 32 * ks + 8 * fq);
; #pragma unroll
;             for (int vt = 0; vt < 4; ++vt) { const bf16x8 a = ldsfrag(ST, 64 * vh + 16 * vt + fr, 272, 32 * ks + 8 * fq); o[vt] = MFMA16(a, bb, o[vt]); } }
;     }
;     if (!RET && DIR == 0) raw_store<128>(X, X.lds + L::RAW, zbr);
.LBB0_521:
	ds_write_b64 v144, v[34:35]
	s_waitcnt lgkmcnt(0)
	s_barrier
	v_add_u32_e32 v173, v118, v43
	ds_read_b128 v[34:37], v145 offset:52224
	ds_read_b128 v[38:41], v173
	ds_read_b128 v[68:71], v146 offset:52224
	ds_read_b128 v[72:75], v147 offset:52224
	ds_read_b128 v[76:79], v148 offset:52224
	s_waitcnt lgkmcnt(2)
	v_mfma_f32_16x16x32_bf16 v[68:71], v[68:71], v[38:41], 0
	ds_read_b128 v[80:83], v150 offset:52224
	ds_read_b128 v[84:87], v149
	v_add_u32_e32 v172, v124, v115
	v_add_u32_e32 v171, v125, v115
	v_mfma_f32_16x16x32_bf16 v[34:37], v[34:37], v[38:41], 0
	v_add_u32_e32 v170, v126, v115
	v_add_u32_e32 v169, v127, v115
	v_add_u32_e32 v168, v124, v116
	s_waitcnt lgkmcnt(3)
	v_mfma_f32_16x16x32_bf16 v[72:75], v[72:75], v[38:41], 0
	v_add_u32_e32 v166, v126, v116
	v_add_u32_e32 v158, v125, v116
	v_add_u32_e32 v167, v127, v116
	s_waitcnt lgkmcnt(2)
	v_mfma_f32_16x16x32_bf16 v[38:41], v[76:79], v[38:41], 0
	ds_read_b128 v[76:79], v151 offset:52224
	v_add_u32_e32 v157, v124, v117
	v_add_u32_e32 v156, v126, v117
	s_waitcnt lgkmcnt(1)
	v_mfma_f32_16x16x32_bf16 v[34:37], v[80:83], v[84:87], v[34:37]
	ds_read_b128 v[80:83], v152 offset:52224
	v_add_u32_e32 v64, s68, v113
	v_add_u32_e32 v155, v125, v117
	s_waitcnt lgkmcnt(1)
	v_mfma_f32_16x16x32_bf16 v[68:71], v[76:79], v[84:87], v[68:71]
	ds_read_b128 v[76:79], v153 offset:52224
	v_add_u32_e32 v61, v127, v117
	v_ashrrev_i32_e32 v65, 31, v64
	s_waitcnt lgkmcnt(1)
	v_mfma_f32_16x16x32_bf16 v[72:75], v[80:83], v[84:87], v[72:75]
	ds_read_b128 v[80:83], v154
	ds_read_b128 v[88:91], v132
	ds_read_b128 v[92:95], v154 offset:4352
	s_or_b32 s60, s62, 1
	v_lshlrev_b64 v[64:65], 8, v[64:65]
	s_waitcnt lgkmcnt(3)
	v_mfma_f32_16x16x32_bf16 v[38:41], v[76:79], v[84:87], v[38:41]
	ds_read_b128 v[76:79], v132 offset:64
	s_ashr_i32 s61, s60, 31
	v_lshl_add_u64 v[64:65], s[24:25], 0, v[64:65]
	s_waitcnt lgkmcnt(2)
	v_mfma_f32_16x16x32_bf16 v[34:37], v[80:83], v[88:91], v[34:37]
	ds_read_b128 v[80:83], v154 offset:8704
	ds_read_b128 v[84:87], v154 offset:13056
	s_lshl_b64 s[60:61], s[60:61], 21
	s_add_u32 s60, s77, s60
	s_waitcnt lgkmcnt(3)
	v_mfma_f32_16x16x32_bf16 v[68:71], v[92:95], v[88:91], v[68:71]
	ds_read_b128 v[92:95], v172
	ds_read_b128 v[96:99], v171
	s_addc_u32 s61, s78, s61
	s_add_u32 s0, s60, s0
	s_waitcnt lgkmcnt(3)
	v_mfma_f32_16x16x32_bf16 v[72:75], v[80:83], v[88:91], v[72:75]
	ds_read_b128 v[80:83], v170
	ds_read_b128 v[100:103], v169
	s_addc_u32 s1, s61, s1
	s_mov_b64 s[64:65], s[20:21]
	s_waitcnt lgkmcnt(4)
	v_mfma_f32_16x16x32_bf16 v[38:41], v[84:87], v[88:91], v[38:41]
	ds_read_b128 v[84:87], v168
	ds_read_b128 v[88:91], v158
	s_waitcnt lgkmcnt(5)
	v_mfma_f32_16x16x32_bf16 v[34:37], v[92:95], v[76:79], v[34:37]
	ds_read_b128 v[92:95], v166
	ds_read_b128 v[104:107], v167
	s_waitcnt lgkmcnt(6)
	v_mfma_f32_16x16x32_bf16 v[68:71], v[96:99], v[76:79], v[68:71]
	ds_read_b128 v[96:99], v132 offset:128
	ds_read_b128 v[108:111], v132 offset:192
	s_waitcnt lgkmcnt(6)
	v_mfma_f32_16x16x32_bf16 v[38:41], v[100:103], v[76:79], v[38:41]
	s_waitcnt lgkmcnt(1)
	v_mfma_f32_16x16x32_bf16 v[34:37], v[84:87], v[96:99], v[34:37]
	v_add_u32_e32 v84, s63, v114
	v_mfma_f32_16x16x32_bf16 v[72:75], v[80:83], v[76:79], v[72:75]
	ds_read_b128 v[80:83], v157
	ds_read_b128 v[174:177], v155
	ds_read_b128 v[76:79], v156
	ds_read_b128 v[100:103], v61
	s_waitcnt vmcnt(1)
	ds_write_b128 v84, v[26:29]
	s_waitcnt vmcnt(0)
	ds_write_b128 v63, v[30:33]
	v_add_u32_e32 v63, s14, v119
	v_mfma_f32_16x16x32_bf16 v[84:87], v[104:107], v[96:99], v[38:41]
	s_waitcnt lgkmcnt(0)
	s_barrier
	v_mfma_f32_16x16x32_bf16 v[26:29], v[88:91], v[96:99], v[68:71]
	s_nop 0
	v_ashrrev_i32_e32 v38, 7, v63
	v_ashrrev_i32_e32 v39, 31, v38
	v_lshlrev_b64 v[68:69], 22, v[38:39]
	s_waitcnt lgkmcnt(5)
	v_mfma_f32_16x16x32_bf16 v[38:41], v[80:83], v[108:111], v[34:37]
	v_mov_b32_e32 v63, v159
	s_nop 1
	v_lshl_add_u64 v[34:35], v[64:65], 0, v[68:69]
	v_mfma_f32_16x16x32_bf16 v[30:33], v[92:95], v[96:99], v[72:75]
	v_lshl_add_u64 v[64:65], v[34:35], 0, v[62:63]
	v_mov_b32_e32 v63, v42
	s_nop 0
	global_load_dwordx2 v[72:73], v[64:65], off
	global_load_dwordx2 v[70:71], v[64:65], off offset:32
	global_load_dwordx2 v[68:69], v[64:65], off offset:64
	s_nop 0
	global_load_dwordx2 v[64:65], v[64:65], off offset:96
	s_waitcnt lgkmcnt(3)
	v_mfma_f32_16x16x32_bf16 v[30:33], v[76:79], v[108:111], v[30:33]
	v_readfirstlane_b32 s62, v63
	v_and_b32_e32 v161, 63, v63
	s_ashr_i32 s70, s62, 6
	v_lshlrev_b32_e32 v63, 2, v161
	v_lshl_or_b32 v88, s70, 11, v63
	v_or_b32_e32 v78, 0x700, v88
	v_or_b32_e32 v80, 0x600, v88
	v_or_b32_e32 v82, 0x500, v88
	v_mfma_f32_16x16x32_bf16 v[34:37], v[174:177], v[108:111], v[26:29]
	v_lshl_add_u64 v[74:75], s[0:1], 0, v[54:55]
	v_add_u32_e32 v79, s63, v78
	v_add_u32_e32 v81, s63, v80
	s_waitcnt lgkmcnt(2)
	v_mfma_f32_16x16x32_bf16 v[26:29], v[100:103], v[108:111], v[84:87]
	v_add_u32_e32 v83, s63, v82
	v_add_u32_e32 v82, s82, v82
	v_lshl_add_u64 v[76:77], s[0:1], 0, v[56:57]
	v_or_b32_e32 v84, 0x400, v88
	v_add_u32_e32 v78, s82, v78
	v_add_u32_e32 v80, s82, v80
	v_add_u32_e32 v85, s63, v84
	v_add_u32_e32 v84, s82, v84
	ds_read_b32 v79, v79
	ds_read_b32 v174, v78
	ds_read_b32 v81, v81
	ds_read_b32 v175, v80
	ds_read_b32 v83, v83
	ds_read_b32 v176, v82
	ds_read_b32 v82, v85
	ds_read_b32 v177, v84
	v_mov_b32_e32 v104, v212
	v_mov_b32_e32 v105, v213
	v_mov_b32_e32 v106, v214
	v_mov_b32_e32 v107, v215
	v_mov_b32_e32 v108, v216
	v_mov_b32_e32 v109, v217
	v_mov_b32_e32 v110, v218
	v_mov_b32_e32 v111, v219
	s_waitcnt lgkmcnt(7)
	v_lshlrev_b32_e32 v78, 16, v79
	v_and_b32_e32 v79, 0xffff0000, v79
	v_mul_f32_e32 v78, 0xbfb8aa3b, v78
	v_mul_f32_e32 v79, 0xbfb8aa3b, v79
	s_waitcnt lgkmcnt(5)
; #define LAS __attribute__((address_space(3)))
; __device__ __forceinline__ unsigned pk2(float lo, float hi) { return pg8::cvt_pk_bf16(lo, hi); }
; __device__ __forceinline__ f32x2v f8lo(unsigned w) { return __builtin_amdgcn_cvt_pk_f32_fp8((int)w, false); }
; __device__ __forceinline__ f32x2v f8hi(unsigned w) { return __builtin_amdgcn_cvt_pk_f32_fp8((int)w, true); }
; __device__ __forceinline__ f32x2v bfpair(unsigned w) { f32x2v r; r.x = __uint_as_float(w << 16); r.y = __uint_as_float(w & 0xffff0000u); return r; }
; __device__ __forceinline__ f32x2v rcp2(f32x2v v) { f32x2v r; r.x = __builtin_amdgcn_rcpf(v.x); r.y = __builtin_amdgcn_rcpf(v.y); return r; }
; template <int DIR, bool NEEDQ>
; __device__ __forceinline__ void gla_prep(lptr rawz, lptr rawq, f32x2v lb, LAS float* seg, int kp, int rg, f32x2v (&c)[8], f32x2v (&qv)[8], f32x2v (&kv)[8]) {
;     f32x2v run = (f32x2v){1.f, 1.f}; const f32x2v oml = 1.0f - lb;
; #pragma unroll
;     for (int i = 0; i < 8; ++i) { const int ii = DIR ? 7 - i : i; const int r = 8 * rg + ii;
;         const f32x2v z = bfpair(*(const LAS unsigned*)(rawz + (r * 128 + 2 * kp) * 2)); f32x2v e; e.x = __expf(-z.x); e.y = __expf(-z.y);
;         const f32x2v f = lb + oml * rcp2(e + 1.0f); run = run * f; kv[ii] = 1.0f - f; c[ii] = run;
;         if (NEEDQ) qv[ii] = bfpair(*(const LAS unsigned*)(rawq + (r * 128 + 2 * kp) * 2)); }
;     *(LAS f32x2v*)(seg + rg * 128 + 2 * kp) = run;
; }
; template <int DK, bool RET, int DIR>
; __device__ __forceinline__ void gla_out_dir(const Ctx& X, int chain, int n, f32x2v lb, const unsigned char* St, f32x4 (&o)[4], const bf16* H, size_t m0, int zbcol) {
;     ...
;         for (int p = 0; p < 2; ++p) { const int idx = X.tid + NTHR * p; const lptr d = ST + (idx >> 3) * 272 + (idx & 7) * 32;
;             v4u a, b; f32x2v f;
;             f = f8lo(sr[p].x); a.x = pk2(f.x, f.y); f = f8hi(sr[p].x); a.y = pk2(f.x, f.y); f = f8lo(sr[p].y); a.z = pk2(f.x, f.y); f = f8hi(sr[p].y); a.w = pk2(f.x, f.y);
;             f = f8lo(sr[p].z); b.x = pk2(f.x, f.y); f = f8hi(sr[p].z); b.y = pk2(f.x, f.y); f = f8lo(sr[p].w); b.z = pk2(f.x, f.y); f = f8hi(sr[p].w); b.w = pk2(f.x, f.y);
;             *(LAS v4u*)d = a; *(LAS v4u*)(d + 16) = b; }
	v_lshlrev_b32_e32 v80, 16, v81
	v_and_b32_e32 v81, 0xffff0000, v81
	v_exp_f32_e32 v78, v78
	v_exp_f32_e32 v79, v79
	v_mul_f32_e32 v80, 0xbfb8aa3b, v80
	v_mul_f32_e32 v81, 0xbfb8aa3b, v81
	v_exp_f32_e32 v80, v80
	v_exp_f32_e32 v81, v81
	v_pk_add_f32 v[78:79], v[78:79], 1.0 op_sel_hi:[1,0]
	v_pk_add_f32 v[86:87], v[66:67], 1.0 op_sel_hi:[1,0] neg_lo:[1,0] neg_hi:[1,0]
	v_rcp_f32_e32 v78, v78
	v_rcp_f32_e32 v79, v79
	v_pk_add_f32 v[80:81], v[80:81], 1.0 op_sel_hi:[1,0]
	v_or_b32_e32 v89, 0x300, v88
	v_rcp_f32_e32 v80, v80
	v_rcp_f32_e32 v81, v81
	v_or_b32_e32 v91, 0x200, v88
	v_pk_fma_f32 v[74:75], v[86:87], v[78:79], v[66:67]
	s_waitcnt lgkmcnt(3)
	v_lshlrev_b32_e32 v78, 16, v83
	v_and_b32_e32 v79, 0xffff0000, v83
	v_add_u32_e32 v90, s63, v89
	v_add_u32_e32 v92, s63, v91
	v_or_b32_e32 v93, 0x100, v88
	v_pk_fma_f32 v[76:77], v[86:87], v[80:81], v[66:67]
	v_mul_f32_e32 v78, 0xbfb8aa3b, v78
	v_mul_f32_e32 v79, 0xbfb8aa3b, v79
	s_waitcnt lgkmcnt(1)
	v_lshlrev_b32_e32 v80, 16, v82
	v_and_b32_e32 v81, 0xffff0000, v82
	v_add_u32_e32 v89, s82, v89
	v_add_u32_e32 v91, s82, v91
	v_add_u32_e32 v94, s63, v93
	v_add_u32_e32 v93, s82, v93
	v_add_u32_e32 v95, s63, v88
	v_add_u32_e32 v88, s82, v88
	ds_read_b32 v90, v90
	ds_read_b32 v178, v89
	ds_read_b32 v92, v92
	ds_read_b32 v179, v91
	ds_read_b32 v96, v94
	ds_read_b32 v180, v93
	ds_read_b32 v98, v95
	ds_read_b32 v181, v88
	v_exp_f32_e32 v78, v78
	v_exp_f32_e32 v79, v79
	v_mul_f32_e32 v80, 0xbfb8aa3b, v80
	v_mul_f32_e32 v81, 0xbfb8aa3b, v81
	s_waitcnt lgkmcnt(7)
	v_lshlrev_b32_e32 v88, 16, v90
	v_and_b32_e32 v89, 0xffff0000, v90
	v_exp_f32_e32 v80, v80
	v_exp_f32_e32 v81, v81
	v_mul_f32_e32 v88, 0xbfb8aa3b, v88
	v_mul_f32_e32 v89, 0xbfb8aa3b, v89
	s_waitcnt lgkmcnt(5)
	v_lshlrev_b32_e32 v90, 16, v92
	v_and_b32_e32 v91, 0xffff0000, v92
	v_exp_f32_e32 v88, v88
	v_exp_f32_e32 v89, v89
	v_mul_f32_e32 v90, 0xbfb8aa3b, v90
	v_mul_f32_e32 v91, 0xbfb8aa3b, v91
	s_waitcnt lgkmcnt(3)
	v_lshlrev_b32_e32 v97, 16, v96
	v_and_b32_e32 v99, 0xffff0000, v96
	v_exp_f32_e32 v90, v90
	v_exp_f32_e32 v91, v91
	v_mul_f32_e32 v96, 0xbfb8aa3b, v97
	v_mul_f32_e32 v97, 0xbfb8aa3b, v99
	s_waitcnt lgkmcnt(1)
	v_lshlrev_b32_e32 v99, 16, v98
	v_and_b32_e32 v100, 0xffff0000, v98
	v_pk_add_f32 v[78:79], v[78:79], 1.0 op_sel_hi:[1,0]
	v_exp_f32_e32 v96, v96
	v_exp_f32_e32 v97, v97
	v_mul_f32_e32 v98, 0xbfb8aa3b, v99
	v_mul_f32_e32 v99, 0xbfb8aa3b, v100
	v_rcp_f32_e32 v82, v78
	v_rcp_f32_e32 v83, v79
	v_pk_add_f32 v[78:79], v[80:81], 1.0 op_sel_hi:[1,0]
	v_exp_f32_e32 v98, v98
	v_exp_f32_e32 v99, v99
	v_rcp_f32_e32 v84, v78
	v_rcp_f32_e32 v85, v79
	v_pk_add_f32 v[88:89], v[88:89], 1.0 op_sel_hi:[1,0]
	v_pk_add_f32 v[96:97], v[96:97], 1.0 op_sel_hi:[1,0]
	v_rcp_f32_e32 v92, v88
	v_rcp_f32_e32 v93, v89
	v_pk_add_f32 v[88:89], v[90:91], 1.0 op_sel_hi:[1,0]
	v_pk_mul_f32 v[78:79], v[74:75], v[76:77]
	v_rcp_f32_e32 v94, v88
	v_rcp_f32_e32 v95, v89
	v_pk_fma_f32 v[82:83], v[86:87], v[82:83], v[66:67]
	v_rcp_f32_e32 v100, v96
	v_rcp_f32_e32 v101, v97
	v_pk_add_f32 v[96:97], v[98:99], 1.0 op_sel_hi:[1,0]
	v_pk_mul_f32 v[80:81], v[78:79], v[82:83]
	v_pk_fma_f32 v[84:85], v[86:87], v[84:85], v[66:67]
	v_rcp_f32_e32 v102, v96
	v_rcp_f32_e32 v103, v97
	v_pk_mul_f32 v[88:89], v[80:81], v[84:85]
	v_pk_fma_f32 v[92:93], v[86:87], v[92:93], v[66:67]
	v_pk_fma_f32 v[94:95], v[86:87], v[94:95], v[66:67]
	v_pk_mul_f32 v[90:91], v[88:89], v[92:93]
	v_pk_fma_f32 v[100:101], v[86:87], v[100:101], v[66:67]
	v_pk_mul_f32 v[96:97], v[90:91], v[94:95]
	s_lshl_b32 s0, s70, 9
	v_pk_mul_f32 v[98:99], v[96:97], v[100:101]
	v_pk_fma_f32 v[66:67], v[86:87], v[102:103], v[66:67]
	s_add_i32 s0, s74, s0
	v_lshlrev_b32_e32 v161, 3, v161
	v_pk_mul_f32 v[102:103], v[98:99], v[66:67]
	v_add_u32_e32 v86, s0, v161
	ds_write_b64 v86, v[102:103]
	s_waitcnt vmcnt(4)
	v_cvt_pk_f32_fp8_e32 v[86:87], v104
	v_cvt_pk_f32_fp8_e32 v[164:165], v105
	v_cvt_pk_f32_fp8_sdwa v[162:163], v104 src0_sel:WORD_1
	v_cvt_pk_f32_fp8_sdwa v[104:105], v105 src0_sel:WORD_1
	v_cvt_pk_bf16_f32 v182, v86, v87
	v_cvt_pk_bf16_f32 v184, v164, v165
	v_cvt_pk_f32_fp8_e32 v[86:87], v106
	v_cvt_pk_f32_fp8_e32 v[164:165], v107
	v_cvt_pk_f32_fp8_sdwa v[186:187], v107 src0_sel:WORD_1
	v_cvt_pk_bf16_f32 v183, v162, v163
	v_cvt_pk_f32_fp8_sdwa v[162:163], v106 src0_sel:WORD_1
	v_cvt_pk_bf16_f32 v185, v104, v105
	v_cvt_pk_bf16_f32 v104, v86, v87
	v_cvt_pk_bf16_f32 v106, v164, v165
	v_cvt_pk_bf16_f32 v107, v186, v187
	s_waitcnt vmcnt(4)
	v_cvt_pk_f32_fp8_e32 v[86:87], v108
	s_waitcnt lgkmcnt(0)
	s_barrier
	v_cvt_pk_bf16_f32 v105, v162, v163
	ds_write_b128 v140, v[182:185]
	ds_write_b128 v140, v[104:107] offset:16
	v_cvt_pk_f32_fp8_sdwa v[106:107], v108 src0_sel:WORD_1
	v_cvt_pk_f32_fp8_e32 v[162:163], v109
	v_cvt_pk_f32_fp8_sdwa v[108:109], v109 src0_sel:WORD_1
	v_cvt_pk_bf16_f32 v104, v86, v87
	v_cvt_pk_f32_fp8_e32 v[86:87], v110
	v_cvt_pk_bf16_f32 v105, v106, v107
	v_cvt_pk_bf16_f32 v106, v162, v163
	v_cvt_pk_f32_fp8_sdwa v[162:163], v110 src0_sel:WORD_1
	v_cvt_pk_f32_fp8_e32 v[164:165], v111
	v_cvt_pk_f32_fp8_sdwa v[182:183], v111 src0_sel:WORD_1
	v_cvt_pk_bf16_f32 v107, v108, v109
	v_cvt_pk_bf16_f32 v108, v86, v87
	v_add_u32_e32 v86, 0, v161
	v_cvt_pk_bf16_f32 v109, v162, v163
	v_cvt_pk_bf16_f32 v110, v164, v165
	v_cvt_pk_bf16_f32 v111, v182, v183
	ds_write_b128 v141, v[104:107]
	ds_write_b128 v141, v[108:111] offset:16
	v_add_u32_e32 v87, 0x14600, v86
	v_add_u32_e32 v106, 0x14400, v86
	v_add_u32_e32 v108, 0x14200, v86
	v_add_u32_e32 v86, 0x14000, v86
	ds_read_b64 v[104:105], v87
	ds_read_b64 v[106:107], v106
	ds_read_b64 v[108:109], v108
	ds_read_b64 v[110:111], v86
	s_sub_i32 s60, 7, s70
	s_and_b32 s1, s60, 3
	s_and_b32 s0, s60, 0x1fffffc
	s_cmp_eq_u32 s1, 0
	v_add_u32_e32 v182, s74, v161
	s_cbranch_scc1 .LBB0_565
	s_lshl_b32 s61, s0, 9
	v_subrev_u32_e32 v86, s61, v182
	ds_read_b64 v[86:87], v86 offset:3584
	s_cmp_lt_u32 s1, 2
	s_cbranch_scc1 .LBB0_524

; #define LAS __attribute__((address_space(3)))
; #define BAR_LDS() do { asm volatile("s_waitcnt lgkmcnt(0)" ::: "memory"); __builtin_amdgcn_s_barrier(); asm volatile("" ::: "memory"); } while (0)
; __device__ __forceinline__ float bf2f(unsigned h) { return __uint_as_float(h << 16); }
; __device__ __forceinline__ unsigned pk2(float lo, float hi) { return pg8::cvt_pk_bf16(lo, hi); }
; __device__ __forceinline__ void ret_out_item(const Ctx& X, const bf16* H, bf16* Y, int l, int it, RetOutRegs& R, bool has_next) {
;     ...
;         const float rstd = __builtin_amdgcn_rsqf((red[(ps * 8 + X.wave) * 16 + fr] + red[(ps * 8 + (X.wave ^ 4)) * 16 + fr]) * (1.0f / 128.0f) + EPS);
; #pragma unroll
;         for (int t = 0; t < 4; ++t) { const int v = 64 * vh + 16 * t + 4 * fq; const f32x4 g4 = *(const f32x4*)(gn + v);
;             const float g0 = bf2f(gw[ps][t].x & 0xffffu), g1 = bf2f(gw[ps][t].x >> 16), g2 = bf2f(gw[ps][t].y & 0xffffu), g3 = bf2f(gw[ps][t].y >> 16);
;             const float y0 = (o[t][0] - mu) * rstd * g4.x * (g0 * __builtin_amdgcn_rcpf(1.0f + __expf(-g0))), y1 = (o[t][1] - mu) * rstd * g4.y * (g1 * __builtin_amdgcn_rcpf(1.0f + __expf(-g1)));
;             const float y2 = (o[t][2] - mu) * rstd * g4.z * (g2 * __builtin_amdgcn_rcpf(1.0f + __expf(-g2))), y3 = (o[t][3] - mu) * rstd * g4.w * (g3 * __builtin_amdgcn_rcpf(1.0f + __expf(-g3)));
;             v2u w; w.x = pk2(y0, y1); w.y = pk2(y2, y3); *(LAS v2u*)(AM + tok * 272 + v * 2) = w; } }
;     BAR_LDS();
; #pragma unroll
;     for (int p = 0; p < 4; ++p) { const int idx = X.tid + NTHR * p, row = idx >> 4, c8 = idx & 15; *(v4u*)(Y + (m0 + row) * D + ycol + 8 * c8) = *(const LAS v4u*)(AM + row * 272 + c8 * 16); }
.LBB0_568:
	s_or_b64 exec, exec, s[0:1]
	s_waitcnt lgkmcnt(0)
	s_barrier
	ds_read_b32 v40, v153 offset:512
	s_waitcnt lgkmcnt(1)
	ds_read_b32 v41, v172 offset:512
	global_load_dwordx4 v[52:55], v[140:141], off
	global_load_dwordx4 v[232:235], v[140:141], off offset:64
	global_load_dwordx4 v[236:239], v[140:141], off offset:128
	global_load_dwordx4 v[240:243], v[140:141], off offset:192
	v_lshlrev_b32_e32 v56, 16, v138
	v_and_b32_e32 v57, 0xffff0000, v138
	s_lshl_b64 s[0:1], s[22:23], 1
	s_waitcnt lgkmcnt(0)
	v_add_f32_e32 v40, v40, v41
	v_mul_f32_e32 v41, 0xbfb8aa3b, v56
	v_fmamk_f32 v40, v40, 0x3c000000, v1
	v_exp_f32_e32 v41, v41
	v_rsq_f32_e32 v40, v40
	s_add_u32 s0, s28, s0
	s_addc_u32 s1, s29, s1
	v_add_f32_e32 v41, 1.0, v41
	v_rcp_f32_e32 v58, v41
	v_pk_mul_f32 v[50:51], v[50:51], v[40:41] op_sel_hi:[1,0]
	v_mul_f32_e32 v41, 0xbfb8aa3b, v57
	v_exp_f32_e32 v41, v41
	s_andn2_b64 vcc, exec, s[18:19]
	v_add_f32_e32 v41, 1.0, v41
	v_rcp_f32_e32 v59, v41
	s_waitcnt vmcnt(3)
	v_pk_mul_f32 v[50:51], v[52:53], v[50:51]
	v_pk_mul_f32 v[52:53], v[58:59], v[56:57]
	s_nop 0
	v_pk_mul_f32 v[50:51], v[52:53], v[50:51]
	v_lshlrev_b32_e32 v52, 16, v139
	v_mul_f32_e32 v41, 0xbfb8aa3b, v52
	v_exp_f32_e32 v41, v41
	v_and_b32_e32 v53, 0xffff0000, v139
	v_cvt_pk_bf16_f32 v50, v50, v51
	v_add_f32_e32 v41, 1.0, v41
	v_rcp_f32_e32 v56, v41
	v_pk_mul_f32 v[48:49], v[48:49], v[40:41] op_sel_hi:[1,0]
	v_mul_f32_e32 v41, 0xbfb8aa3b, v53
	v_exp_f32_e32 v41, v41
	v_pk_mul_f32 v[48:49], v[54:55], v[48:49]
	v_add_f32_e32 v41, 1.0, v41
	v_rcp_f32_e32 v57, v41
	v_add_u32_e32 v41, v189, v185
	v_pk_mul_f32 v[52:53], v[56:57], v[52:53]
	s_nop 0
	v_pk_mul_f32 v[48:49], v[52:53], v[48:49]
	v_lshlrev_b32_e32 v52, 16, v136
	v_cvt_pk_bf16_f32 v51, v48, v49
	ds_write_b64 v41, v[50:51]
	v_mul_f32_e32 v41, 0xbfb8aa3b, v52
	v_exp_f32_e32 v41, v41
	v_and_b32_e32 v53, 0xffff0000, v136
	v_add_f32_e32 v41, 1.0, v41
	v_rcp_f32_e32 v54, v41
	v_pk_mul_f32 v[46:47], v[46:47], v[40:41] op_sel_hi:[1,0]
	v_mul_f32_e32 v41, 0xbfb8aa3b, v53
	v_exp_f32_e32 v41, v41
	s_waitcnt vmcnt(2)
	v_pk_mul_f32 v[46:47], v[232:233], v[46:47]
	v_add_f32_e32 v41, 1.0, v41
	v_rcp_f32_e32 v55, v41
	s_nop 0
	v_pk_mul_f32 v[48:49], v[54:55], v[52:53]
	s_nop 0
	v_pk_mul_f32 v[46:47], v[48:49], v[46:47]
	v_lshlrev_b32_e32 v48, 16, v137
	v_mul_f32_e32 v41, 0xbfb8aa3b, v48
	v_exp_f32_e32 v41, v41
	v_and_b32_e32 v49, 0xffff0000, v137
	v_cvt_pk_bf16_f32 v46, v46, v47
	v_add_f32_e32 v41, 1.0, v41
	v_rcp_f32_e32 v52, v41
	v_pk_mul_f32 v[44:45], v[44:45], v[40:41] op_sel_hi:[1,0]
	v_mul_f32_e32 v41, 0xbfb8aa3b, v49
	v_exp_f32_e32 v41, v41
	v_pk_mul_f32 v[44:45], v[234:235], v[44:45]
	v_add_f32_e32 v41, 1.0, v41
	v_rcp_f32_e32 v53, v41
	v_add_u32_e32 v41, v189, v186
	v_pk_mul_f32 v[48:49], v[52:53], v[48:49]
	s_nop 0
	v_pk_mul_f32 v[44:45], v[48:49], v[44:45]
	v_lshlrev_b32_e32 v48, 16, v134
	v_cvt_pk_bf16_f32 v47, v44, v45
	ds_write_b64 v41, v[46:47]
	v_mul_f32_e32 v41, 0xbfb8aa3b, v48
	v_exp_f32_e32 v41, v41
	v_and_b32_e32 v49, 0xffff0000, v134
	v_add_f32_e32 v41, 1.0, v41
	v_rcp_f32_e32 v50, v41
	v_pk_mul_f32 v[36:37], v[36:37], v[40:41] op_sel_hi:[1,0]
	v_mul_f32_e32 v41, 0xbfb8aa3b, v49
	v_exp_f32_e32 v41, v41
	s_waitcnt vmcnt(1)
	v_pk_mul_f32 v[36:37], v[36:37], v[236:237]
	v_add_f32_e32 v41, 1.0, v41
	v_rcp_f32_e32 v51, v41
	s_nop 0
	v_pk_mul_f32 v[44:45], v[50:51], v[48:49]
	s_nop 0
	v_pk_mul_f32 v[36:37], v[44:45], v[36:37]
	v_lshlrev_b32_e32 v44, 16, v135
	v_mul_f32_e32 v41, 0xbfb8aa3b, v44
	v_exp_f32_e32 v41, v41
	v_and_b32_e32 v45, 0xffff0000, v135
	v_cvt_pk_bf16_f32 v36, v36, v37
	v_add_f32_e32 v41, 1.0, v41
	v_rcp_f32_e32 v48, v41
	v_pk_mul_f32 v[34:35], v[34:35], v[40:41] op_sel_hi:[1,0]
	v_mul_f32_e32 v41, 0xbfb8aa3b, v45
	v_exp_f32_e32 v41, v41
	v_pk_mul_f32 v[34:35], v[34:35], v[238:239]
	v_add_f32_e32 v41, 1.0, v41
	v_rcp_f32_e32 v49, v41
	s_nop 0
	v_pk_mul_f32 v[44:45], v[48:49], v[44:45]
	s_nop 0
	v_pk_mul_f32 v[34:35], v[44:45], v[34:35]
	v_lshlrev_b32_e32 v44, 16, v132
	v_cvt_pk_bf16_f32 v37, v34, v35
	v_add_u32_e32 v34, v189, v187
	ds_write_b64 v34, v[36:37]
	v_mul_f32_e32 v41, 0xbfb8aa3b, v44
	v_exp_f32_e32 v41, v41
	v_and_b32_e32 v45, 0xffff0000, v132
	v_add_f32_e32 v41, 1.0, v41
	v_rcp_f32_e32 v46, v41
	v_pk_mul_f32 v[42:43], v[42:43], v[40:41] op_sel_hi:[1,0]
	v_mul_f32_e32 v41, 0xbfb8aa3b, v45
	v_exp_f32_e32 v41, v41
	s_waitcnt vmcnt(0)
	v_pk_mul_f32 v[34:35], v[42:43], v[240:241]
	v_add_f32_e32 v41, 1.0, v41
	v_rcp_f32_e32 v47, v41
	s_nop 0
	v_pk_mul_f32 v[42:43], v[46:47], v[44:45]
	s_nop 0
	v_pk_mul_f32 v[34:35], v[42:43], v[34:35]
	v_lshlrev_b32_e32 v42, 16, v133
	v_mul_f32_e32 v41, 0xbfb8aa3b, v42
	v_exp_f32_e32 v41, v41
	v_and_b32_e32 v43, 0xffff0000, v133
	v_cvt_pk_bf16_f32 v34, v34, v35
	v_add_f32_e32 v41, 1.0, v41
	v_pk_mul_f32 v[38:39], v[38:39], v[40:41] op_sel_hi:[1,0]
	v_rcp_f32_e32 v44, v41
	v_pk_mul_f32 v[36:37], v[38:39], v[242:243]
	v_mul_f32_e32 v38, 0xbfb8aa3b, v43
	v_exp_f32_e32 v38, v38
	s_nop 0
	v_add_f32_e32 v38, 1.0, v38
	v_rcp_f32_e32 v45, v38
	s_nop 0
	v_pk_mul_f32 v[38:39], v[44:45], v[42:43]
	s_nop 0
	v_pk_mul_f32 v[36:37], v[38:39], v[36:37]
	v_lshl_add_u64 v[38:39], s[12:13], 0, v[106:107]
	v_cvt_pk_bf16_f32 v35, v36, v37
	v_add_u32_e32 v36, v189, v188
	ds_write_b64 v36, v[34:35]
	s_waitcnt lgkmcnt(0)
	s_barrier
	ds_read_b128 v[34:37], v210
	v_lshlrev_b64 v[38:39], 12, v[38:39]
	v_lshl_add_u64 v[38:39], s[0:1], 0, v[38:39]
	v_lshl_add_u64 v[38:39], v[38:39], 0, v[158:159]
	s_waitcnt lgkmcnt(0)
	global_store_dwordx4 v[38:39], v[34:37], off offset:1536
	ds_read_b128 v[34:37], v211
	v_lshl_add_u64 v[38:39], s[12:13], 0, v[108:109]
	v_lshlrev_b64 v[38:39], 12, v[38:39]
	v_lshl_add_u64 v[38:39], s[0:1], 0, v[38:39]
	v_lshl_add_u64 v[38:39], v[38:39], 0, v[158:159]
	s_waitcnt lgkmcnt(0)
	global_store_dwordx4 v[38:39], v[34:37], off offset:1536
	ds_read_b128 v[34:37], v212
	v_lshl_add_u64 v[38:39], s[12:13], 0, v[110:111]
	v_lshlrev_b64 v[38:39], 12, v[38:39]
	v_lshl_add_u64 v[38:39], s[0:1], 0, v[38:39]
	v_lshl_add_u64 v[38:39], v[38:39], 0, v[158:159]
	s_waitcnt lgkmcnt(0)
	global_store_dwordx4 v[38:39], v[34:37], off offset:1536
	ds_read_b128 v[34:37], v213
	v_lshl_add_u64 v[38:39], s[12:13], 0, v[112:113]
	v_lshlrev_b64 v[38:39], 12, v[38:39]
	v_lshl_add_u64 v[38:39], s[0:1], 0, v[38:39]
	v_lshl_add_u64 v[38:39], v[38:39], 0, v[158:159]
	s_waitcnt lgkmcnt(0)
	global_store_dwordx4 v[38:39], v[34:37], off offset:1536
	s_waitcnt lgkmcnt(0)
	s_barrier
	s_mov_b32 s0, s38
	s_cbranch_vccz .LBB0_597

; #define LAS __attribute__((address_space(3)))
; __device__ __forceinline__ float bf2f(unsigned h) { return __uint_as_float(h << 16); }
; __device__ __forceinline__ unsigned pk2(float lo, float hi) { return pg8::cvt_pk_bf16(lo, hi); }
; #define MFMA16(a, b, c) __builtin_amdgcn_mfma_f32_16x16x32_bf16((a), (b), (c), 0, 0, 0)
; __device__ __forceinline__ void ret_out_item(const Ctx& X, const bf16* H, bf16* Y, int l, int it, RetOutRegs& R, bool has_next) {
;     ...
;     for (int ps = 0; ps < 2; ++ps) { const int tok = 16 * (tbq + 4 * ps) + fr; f32x4 o[4];
; #pragma unroll
;         for (int t = 0; t < 4; ++t) o[t] = (f32x4){0.f, 0.f, 0.f, 0.f};
; #pragma unroll
;         for (int ks = 0; ks < 4; ++ks) { const bf16x8 bb = ldsfrag(AM, tok, 272, 32 * ks + 8 * fq);
; #pragma unroll
;             for (int vt = 0; vt < 4; ++vt) { const bf16x8 a = vtfrag(VT, 64 * vh + 16 * vt + fr, 272, 32 * ks + 8 * fq); o[vt] = MFMA16(a, bb, o[vt]); } }
;     ...
;         const float rstd = __builtin_amdgcn_rsqf((red[(ps * 8 + X.wave) * 16 + fr] + red[(ps * 8 + (X.wave ^ 4)) * 16 + fr]) * (1.0f / 128.0f) + EPS);
; #pragma unroll
;         for (int t = 0; t < 4; ++t) { const int v = 64 * vh + 16 * t + 4 * fq; const f32x4 g4 = *(const f32x4*)(gn + v);
;             const float g0 = bf2f(gw[ps][t].x & 0xffffu), g1 = bf2f(gw[ps][t].x >> 16), g2 = bf2f(gw[ps][t].y & 0xffffu), g3 = bf2f(gw[ps][t].y >> 16);
;             const float y0 = (o[t][0] - mu) * rstd * g4.x * (g0 * __builtin_amdgcn_rcpf(1.0f + __expf(-g0))), y1 = (o[t][1] - mu) * rstd * g4.y * (g1 * __builtin_amdgcn_rcpf(1.0f + __expf(-g1)));
;             const float y2 = (o[t][2] - mu) * rstd * g4.z * (g2 * __builtin_amdgcn_rcpf(1.0f + __expf(-g2))), y3 = (o[t][3] - mu) * rstd * g4.w * (g3 * __builtin_amdgcn_rcpf(1.0f + __expf(-g3)));
;             v2u w; w.x = pk2(y0, y1); w.y = pk2(y2, y3); *(LAS v2u*)(AM + tok * 272 + v * 2) = w; } }
.LBB0_593:
	s_or_b64 exec, exec, s[24:25]
	s_ashr_i32 s23, s22, 31
	s_waitcnt lgkmcnt(0)
	s_barrier
	v_add_u32_e32 v153, s36, v174
	v_add_u32_e32 v172, s37, v174
	s_add_u32 s24, s0, s16
	ds_read_b32 v152, v153
	ds_read_b32 v162, v172
	s_addc_u32 s25, s1, s17
	s_lshl_b64 s[0:1], s[22:23], 2
	s_add_u32 s0, s24, s0
	s_addc_u32 s1, s25, s1
	s_waitcnt lgkmcnt(2)
	v_lshl_add_u64 v[140:141], v[114:115], 2, s[0:1]
	s_waitcnt lgkmcnt(0)
	v_add_f32_e32 v152, v152, v162
	global_load_dwordx4 v[162:165], v[140:141], off
	global_load_dwordx4 v[236:239], v[140:141], off offset:64
	global_load_dwordx4 v[240:243], v[140:141], off offset:128
	global_load_dwordx4 v[244:247], v[140:141], off offset:192
	s_waitcnt vmcnt(8)
	v_lshlrev_b32_e32 v232, 16, v154
	v_and_b32_e32 v233, 0xffff0000, v154
	v_mul_f32_e32 v154, 0xbfb8aa3b, v232
	v_exp_f32_e32 v154, v154
	v_fmamk_f32 v152, v152, 0x3c000000, v1
	v_rsq_f32_e32 v152, v152
	v_mul_f32_e32 v121, v121, v191
	v_add_f32_e32 v154, 1.0, v154
	v_rcp_f32_e32 v234, v154
	v_mul_f32_e32 v154, 0xbfb8aa3b, v233
	v_exp_f32_e32 v154, v154
	v_pk_mul_f32 v[170:171], v[170:171], v[152:153] op_sel_hi:[1,0]
	v_pk_mul_f32 v[168:169], v[168:169], v[152:153] op_sel_hi:[1,0]
	v_pk_mul_f32 v[166:167], v[166:167], v[152:153] op_sel_hi:[1,0]
	v_add_f32_e32 v154, 1.0, v154
	v_rcp_f32_e32 v235, v154
	v_lshlrev_b32_e32 v154, 16, v155
	v_and_b32_e32 v155, 0xffff0000, v155
	v_pk_mul_f32 v[156:157], v[156:157], v[152:153] op_sel_hi:[1,0]
	v_pk_mul_f32 v[100:101], v[100:101], v[152:153] op_sel_hi:[1,0]
	v_pk_mul_f32 v[98:99], v[98:99], v[152:153] op_sel_hi:[1,0]
	v_pk_mul_f32 v[150:151], v[150:151], v[152:153] op_sel_hi:[1,0]
	s_waitcnt vmcnt(3)
	v_pk_mul_f32 v[162:163], v[162:163], v[170:171]
	v_pk_mul_f32 v[170:171], v[234:235], v[232:233]
	v_pk_mul_f32 v[164:165], v[164:165], v[168:169]
	v_pk_mul_f32 v[162:163], v[170:171], v[162:163]
	v_mul_f32_e32 v170, 0xbfb8aa3b, v154
	v_mul_f32_e32 v168, 0xbfb8aa3b, v155
	v_exp_f32_e32 v170, v170
	v_exp_f32_e32 v168, v168
	v_cvt_pk_bf16_f32 v162, v162, v163
	v_add_f32_e32 v170, 1.0, v170
	v_add_f32_e32 v168, 1.0, v168
	v_rcp_f32_e32 v170, v170
	v_rcp_f32_e32 v171, v168
	s_nop 0
	v_pk_mul_f32 v[154:155], v[170:171], v[154:155]
	s_nop 0
	v_pk_mul_f32 v[154:155], v[154:155], v[164:165]
	s_nop 0
	v_cvt_pk_bf16_f32 v163, v154, v155
	v_add_u32_e32 v154, v175, v185
	ds_write_b64 v154, v[162:163]
	v_lshlrev_b32_e32 v154, 16, v146
	v_and_b32_e32 v155, 0xffff0000, v146
	v_mul_f32_e32 v146, 0xbfb8aa3b, v154
	v_exp_f32_e32 v146, v146
	s_waitcnt vmcnt(2)
	v_pk_mul_f32 v[162:163], v[236:237], v[166:167]
	v_add_f32_e32 v146, 1.0, v146
	v_rcp_f32_e32 v168, v146
	v_mul_f32_e32 v146, 0xbfb8aa3b, v155
	v_exp_f32_e32 v146, v146
	v_pk_mul_f32 v[156:157], v[238:239], v[156:157]
	v_add_f32_e32 v146, 1.0, v146
	v_rcp_f32_e32 v169, v146
	v_lshlrev_b32_e32 v146, 16, v147
	v_and_b32_e32 v147, 0xffff0000, v147
	v_pk_mul_f32 v[154:155], v[168:169], v[154:155]
	s_nop 0
	v_pk_mul_f32 v[154:155], v[154:155], v[162:163]
	v_mul_f32_e32 v162, 0xbfb8aa3b, v146
	v_mul_f32_e32 v163, 0xbfb8aa3b, v147
	v_exp_f32_e32 v162, v162
	v_exp_f32_e32 v163, v163
	v_cvt_pk_bf16_f32 v154, v154, v155
	v_add_f32_e32 v162, 1.0, v162
	v_add_f32_e32 v163, 1.0, v163
	v_rcp_f32_e32 v162, v162
	v_rcp_f32_e32 v163, v163
	s_nop 0
	v_pk_mul_f32 v[146:147], v[162:163], v[146:147]
	s_nop 0
	v_pk_mul_f32 v[146:147], v[146:147], v[156:157]
	s_nop 0
	v_cvt_pk_bf16_f32 v155, v146, v147
	v_add_u32_e32 v146, v175, v186
	ds_write_b64 v146, v[154:155]
	v_lshlrev_b32_e32 v146, 16, v144
	v_and_b32_e32 v147, 0xffff0000, v144
	v_mul_f32_e32 v144, 0xbfb8aa3b, v146
	v_exp_f32_e32 v144, v144
	s_waitcnt vmcnt(1)
	v_pk_mul_f32 v[100:101], v[100:101], v[240:241]
	v_add_f32_e32 v144, 1.0, v144
	v_rcp_f32_e32 v162, v144
	v_mul_f32_e32 v144, 0xbfb8aa3b, v147
	v_exp_f32_e32 v144, v144
	v_pk_mul_f32 v[98:99], v[98:99], v[242:243]
	v_add_f32_e32 v144, 1.0, v144
	v_rcp_f32_e32 v163, v144
	v_lshlrev_b32_e32 v144, 16, v145
	v_and_b32_e32 v145, 0xffff0000, v145
	v_pk_mul_f32 v[146:147], v[162:163], v[146:147]
	s_nop 0
	v_pk_mul_f32 v[100:101], v[146:147], v[100:101]
	v_mul_f32_e32 v146, 0xbfb8aa3b, v144
	v_mul_f32_e32 v147, 0xbfb8aa3b, v145
	v_exp_f32_e32 v146, v146
	v_exp_f32_e32 v147, v147
	v_cvt_pk_bf16_f32 v100, v100, v101
	v_add_f32_e32 v146, 1.0, v146
	v_add_f32_e32 v147, 1.0, v147
	v_rcp_f32_e32 v146, v146
	v_rcp_f32_e32 v147, v147
	s_nop 0
	v_pk_mul_f32 v[144:145], v[146:147], v[144:145]
	s_nop 0
	v_pk_mul_f32 v[98:99], v[144:145], v[98:99]
	v_lshlrev_b32_e32 v144, 16, v142
	v_cvt_pk_bf16_f32 v101, v98, v99
	v_add_u32_e32 v98, v175, v187
	ds_write_b64 v98, v[100:101]
	v_and_b32_e32 v145, 0xffff0000, v142
	v_mul_f32_e32 v142, 0xbfb8aa3b, v144
	v_exp_f32_e32 v142, v142
	s_waitcnt vmcnt(0)
	v_pk_mul_f32 v[98:99], v[150:151], v[244:245]
	v_add_f32_e32 v142, 1.0, v142
	v_rcp_f32_e32 v146, v142
	v_mul_f32_e32 v142, 0xbfb8aa3b, v145
	v_exp_f32_e32 v142, v142
	v_add_u32_e32 v150, v189, v176
	v_add_f32_e32 v142, 1.0, v142
	v_rcp_f32_e32 v147, v142
	v_lshlrev_b32_e32 v142, 16, v143
	v_and_b32_e32 v143, 0xffff0000, v143
	v_pk_mul_f32 v[144:145], v[146:147], v[144:145]
	s_nop 0
	v_pk_mul_f32 v[98:99], v[144:145], v[98:99]
	v_mul_f32_e32 v144, 0xbfb8aa3b, v142
	v_mul_f32_e32 v145, 0xbfb8aa3b, v143
	v_exp_f32_e32 v144, v144
	v_exp_f32_e32 v145, v145
	v_pk_mul_f32 v[146:147], v[148:149], v[152:153] op_sel_hi:[1,0]
	v_cvt_pk_bf16_f32 v98, v98, v99
	v_add_f32_e32 v144, 1.0, v144
	v_add_f32_e32 v145, 1.0, v145
	v_rcp_f32_e32 v144, v144
	v_rcp_f32_e32 v145, v145
	v_pk_mul_f32 v[100:101], v[146:147], v[246:247]
	v_pk_mul_f32 v[142:143], v[144:145], v[142:143]
	s_nop 0
	v_pk_mul_f32 v[100:101], v[142:143], v[100:101]
	s_nop 0
	v_cvt_pk_bf16_f32 v99, v100, v101
	v_add_u32_e32 v100, v175, v188
	ds_write_b64 v100, v[98:99]
	v_add_u32_e32 v98, v189, v119
	ds_read_b128 v[98:101], v98
	ds_read_b128 v[142:145], v214 offset:36864
	ds_read_b128 v[146:149], v215 offset:36864
	ds_read_b128 v[154:157], v216 offset:36864
	ds_read_b128 v[162:165], v217 offset:36864
	s_waitcnt lgkmcnt(3)
; #define MFMA16(a, b, c) __builtin_amdgcn_mfma_f32_16x16x32_bf16((a), (b), (c), 0, 0, 0)
; __device__ __forceinline__ void ret_out_item(const Ctx& X, const bf16* H, bf16* Y, int l, int it, RetOutRegs& R, bool has_next) {
;     ...
;     for (int ps = 0; ps < 2; ++ps) { const int tok = 16 * (tbq + 4 * ps) + fr; f32x4 o[4];
; #pragma unroll
;         for (int t = 0; t < 4; ++t) o[t] = (f32x4){0.f, 0.f, 0.f, 0.f};
; #pragma unroll
;         for (int ks = 0; ks < 4; ++ks) { const bf16x8 bb = ldsfrag(AM, tok, 272, 32 * ks + 8 * fq);
; #pragma unroll
;             for (int vt = 0; vt < 4; ++vt) { const bf16x8 a = vtfrag(VT, 64 * vh + 16 * vt + fr, 272, 32 * ks + 8 * fq); o[vt] = MFMA16(a, bb, o[vt]); } }
;         const bf16x8 bq0 = ldsfrag(Q, tok, 144, 8 * fq), bq1 = ldsfrag(Q, tok, 144, 32 + 8 * fq);
;         const float cf = __builtin_amdgcn_exp2f((float)(tok + 1) * l2f), cb = __builtin_amdgcn_exp2f((float)(RCH - tok) * l2b);
;         {
;             f32x4 tf[4];
; #pragma unroll
;             for (int vt = 0; vt < 4; ++vt) { tf[vt] = MFMA16(sff[0][vt], bq0, ((f32x4){0.f, 0.f, 0.f, 0.f})); tf[vt] = MFMA16(sff[1][vt], bq1, tf[vt]); }
; #pragma unroll
;             for (int t = 0; t < 4; ++t) o[t] = o[t] + tf[t] * cf;
; #pragma unroll
;             for (int vt = 0; vt < 4; ++vt) { tf[vt] = MFMA16(sfb[0][vt], bq0, ((f32x4){0.f, 0.f, 0.f, 0.f})); tf[vt] = MFMA16(sfb[1][vt], bq1, tf[vt]); }
; #pragma unroll
;             for (int t = 0; t < 4; ++t) o[t] = o[t] + tf[t] * cb;
;         }
;         float s_ = 0.f;
; #pragma unroll
;         for (int t = 0; t < 4; ++t) s_ += (o[t][0] + o[t][1]) + (o[t][2] + o[t][3]);
;         s_ += __shfl_xor(s_, 16); s_ += __shfl_xor(s_, 32);
;         if (fq == 0) red[512 + (ps * 8 + X.wave) * 16 + fr] = s_;
	v_mfma_f32_16x16x32_bf16 v[142:145], v[142:145], v[98:101], 0
	s_waitcnt lgkmcnt(2)
	v_mfma_f32_16x16x32_bf16 v[146:149], v[146:149], v[98:101], 0
	s_waitcnt lgkmcnt(1)
	v_mfma_f32_16x16x32_bf16 v[154:157], v[154:157], v[98:101], 0
	s_waitcnt lgkmcnt(0)
	v_mfma_f32_16x16x32_bf16 v[98:101], v[162:165], v[98:101], 0
	ds_read_b128 v[162:165], v150
	ds_read_b128 v[166:169], v218 offset:36864
	v_add_u32_e32 v150, v189, v177
	s_waitcnt lgkmcnt(0)
	v_mfma_f32_16x16x32_bf16 v[142:145], v[166:169], v[162:165], v[142:145]
	ds_read_b128 v[166:169], v219 offset:36864
	s_waitcnt lgkmcnt(0)
	v_mfma_f32_16x16x32_bf16 v[146:149], v[166:169], v[162:165], v[146:149]
	ds_read_b128 v[166:169], v220 offset:36864
	s_waitcnt lgkmcnt(0)
	v_mfma_f32_16x16x32_bf16 v[154:157], v[166:169], v[162:165], v[154:157]
	ds_read_b128 v[166:169], v221 offset:36864
	s_waitcnt lgkmcnt(0)
	v_mfma_f32_16x16x32_bf16 v[98:101], v[166:169], v[162:165], v[98:101]
	ds_read_b128 v[162:165], v150
	ds_read_b128 v[166:169], v222 offset:36864
	v_add_u32_e32 v150, v189, v178
	s_waitcnt lgkmcnt(0)
	v_mfma_f32_16x16x32_bf16 v[142:145], v[166:169], v[162:165], v[142:145]
	ds_read_b128 v[166:169], v223 offset:36864
	s_waitcnt lgkmcnt(0)
	v_mfma_f32_16x16x32_bf16 v[146:149], v[166:169], v[162:165], v[146:149]
	ds_read_b128 v[166:169], v224 offset:36864
	s_waitcnt lgkmcnt(0)
	v_mfma_f32_16x16x32_bf16 v[154:157], v[166:169], v[162:165], v[154:157]
	ds_read_b128 v[166:169], v225 offset:36864
	s_waitcnt lgkmcnt(0)
	v_mfma_f32_16x16x32_bf16 v[98:101], v[166:169], v[162:165], v[98:101]
	ds_read_b128 v[162:165], v150
	ds_read_b128 v[166:169], v226 offset:36864
	v_mul_f32_e32 v150, v230, v190
	s_waitcnt lgkmcnt(0)
	v_mfma_f32_16x16x32_bf16 v[142:145], v[166:169], v[162:165], v[142:145]
	ds_read_b128 v[166:169], v227 offset:36864
	s_waitcnt lgkmcnt(0)
	v_mfma_f32_16x16x32_bf16 v[146:149], v[166:169], v[162:165], v[146:149]
	ds_read_b128 v[166:169], v228 offset:36864
	s_waitcnt lgkmcnt(0)
	v_mfma_f32_16x16x32_bf16 v[154:157], v[166:169], v[162:165], v[154:157]
	ds_read_b128 v[166:169], v229 offset:36864
	s_waitcnt lgkmcnt(0)
	v_mfma_f32_16x16x32_bf16 v[98:101], v[166:169], v[162:165], v[98:101]
	ds_read_b128 v[162:165], v209
	ds_read_b128 v[166:169], v209 offset:64
	s_waitcnt lgkmcnt(1)
	v_mfma_f32_16x16x32_bf16 v[66:69], v[66:69], v[162:165], 0
	v_mfma_f32_16x16x32_bf16 v[70:73], v[70:73], v[162:165], 0
	v_mfma_f32_16x16x32_bf16 v[78:81], v[78:81], v[162:165], 0
	v_mfma_f32_16x16x32_bf16 v[38:41], v[38:41], v[162:165], 0
	v_mfma_f32_16x16x32_bf16 v[46:49], v[46:49], v[162:165], 0
	v_mfma_f32_16x16x32_bf16 v[34:37], v[34:37], v[162:165], 0
	v_mfma_f32_16x16x32_bf16 v[74:77], v[74:77], v[162:165], 0
	s_waitcnt lgkmcnt(0)
	v_mfma_f32_16x16x32_bf16 v[66:69], v[82:85], v[166:169], v[66:69]
	v_exp_f32_e32 v82, v150
	v_mfma_f32_16x16x32_bf16 v[42:45], v[42:45], v[162:165], 0
	v_mfma_f32_16x16x32_bf16 v[70:73], v[86:89], v[166:169], v[70:73]
	s_nop 4
	v_fma_f32 v68, v82, v68, v144
	v_fma_f32 v69, v82, v69, v145
	v_pk_fma_f32 v[66:67], v[82:83], v[66:67], v[142:143] op_sel_hi:[0,1,1]
	v_mfma_f32_16x16x32_bf16 v[78:81], v[94:97], v[166:169], v[78:81]
	v_mfma_f32_16x16x32_bf16 v[38:41], v[58:61], v[166:169], v[38:41]
	v_fma_f32 v72, v82, v72, v148
	v_fma_f32 v73, v82, v73, v149
	v_pk_fma_f32 v[70:71], v[82:83], v[70:71], v[146:147] op_sel_hi:[0,1,1]
	s_nop 3
	v_pk_fma_f32 v[78:79], v[82:83], v[78:79], v[98:99] op_sel_hi:[0,1,1]
	v_mfma_f32_16x16x32_bf16 v[58:61], v[62:65], v[166:169], v[46:49]
	v_exp_f32_e32 v62, v121
	v_pk_fma_f32 v[80:81], v[82:83], v[80:81], v[100:101] op_sel_hi:[0,1,1]
	v_mfma_f32_16x16x32_bf16 v[48:51], v[50:53], v[166:169], v[34:37]
	v_fma_f32 v46, v62, v38, v66
	v_fma_f32 v47, v62, v39, v67
	v_mfma_f32_16x16x32_bf16 v[74:77], v[90:93], v[166:169], v[74:77]
	s_nop 1
	v_fma_f32 v36, v62, v60, v72
	v_fma_f32 v37, v62, v61, v73
	s_nop 0
	v_pk_fma_f32 v[38:39], v[62:63], v[50:51], v[80:81] op_sel_hi:[0,1,1]
	v_add_f32_e32 v50, v36, v37
	v_mfma_f32_16x16x32_bf16 v[54:57], v[54:57], v[166:169], v[42:45]
	s_nop 2
	v_fma_f32 v42, v62, v40, v68
	v_fma_f32 v43, v62, v41, v69
	v_pk_fma_f32 v[44:45], v[62:63], v[58:59], v[70:71] op_sel_hi:[0,1,1]
	v_pk_fma_f32 v[40:41], v[62:63], v[48:49], v[78:79] op_sel_hi:[0,1,1]
	v_add_f32_e32 v48, v46, v47
	v_add_f32_e32 v49, v42, v43
	v_pk_fma_f32 v[76:77], v[82:83], v[76:77], v[156:157] op_sel_hi:[0,1,1]
	v_pk_fma_f32 v[74:75], v[82:83], v[74:75], v[154:155] op_sel_hi:[0,1,1]
	v_add_f32_e32 v48, v48, v49
	v_add_f32_e32 v49, v44, v45
	v_pk_fma_f32 v[34:35], v[62:63], v[56:57], v[76:77] op_sel_hi:[0,1,1]
	v_pk_fma_f32 v[52:53], v[62:63], v[54:55], v[74:75] op_sel_hi:[0,1,1]
	v_add_f32_e32 v48, 0, v48
	v_add_f32_e32 v49, v49, v50
	v_add_f32_e32 v48, v48, v49
	v_add_f32_e32 v49, v52, v53
	v_add_f32_e32 v50, v34, v35
	v_add_f32_e32 v49, v49, v50
	v_add_f32_e32 v48, v48, v49
	v_add_f32_e32 v49, v40, v41
	v_add_f32_e32 v50, v38, v39
	v_add_f32_e32 v49, v49, v50
	v_add_f32_e32 v48, v48, v49
	ds_bpermute_b32 v49, v131, v48
	s_waitcnt lgkmcnt(0)
	v_add_f32_e32 v48, v48, v49
	ds_bpermute_b32 v49, v231, v48
	s_and_saveexec_b64 s[0:1], s[40:41]
	s_cbranch_execz .LBB0_595
	s_waitcnt lgkmcnt(0)
	v_add_f32_e32 v48, v48, v49
	ds_write_b32 v192, v48
